# attention: one static s_setprio 1 for waves 4-7 for the whole phase (strategy 4)
# baseline (speedup 1.0000x reference)
.LBB0_1140:
	s_cmp_gt_i32 s86, 8
	s_cselect_b64 s[0:1], -1, 0
	s_cmp_lt_i32 s87, 9
	s_cselect_b64 s[2:3], -1, 0
	s_or_b64 s[0:1], s[0:1], s[2:3]
	s_and_b64 vcc, exec, s[0:1]
	s_cbranch_vccnz .LBB0_1228
	v_readfirstlane_b32 s0, v204
	s_nop 0
	s_cmpk_lt_u32 s0, 0x100
	s_cbranch_scc1 .Lattn_prio_skip
	s_setprio 1
.Lattn_prio_skip:
	s_cmpk_gt_i32 s83, 0x3ff
	s_cbranch_scc1 .LBB0_1174
	s_add_u32 s2, s76, 0xc000000
	s_addc_u32 s3, s77, 0
	v_readlane_b32 s0, v253, 0
	s_add_u32 s24, s76, 0x6000000
	v_readlane_b32 s1, v253, 1
	s_addc_u32 s25, s77, 0
	s_load_dwordx2 s[10:11], s[0:1], 0x58
	s_add_u32 s26, s76, 0x13c00000
	v_mbcnt_lo_u32_b32 v0, -1, 0
	s_addc_u32 s27, s77, 0
	v_mbcnt_hi_u32_b32 v179, -1, v0
	s_add_u32 s8, s76, 0x19300000
	v_and_b32_e32 v0, 64, v179
	s_addc_u32 s9, s77, 0
	s_add_i32 s12, s83, 0xfffffe00
	s_mov_b32 s15, 0
	s_mov_b32 s28, 0x18000
	s_movk_i32 s29, 0x1800
	s_movk_i32 s30, 0x180
	s_movk_i32 s31, 0xffe0
	v_mov_b32_e32 v165, 0
	v_mov_b32_e32 v178, 0x358637bd
	s_mov_b32 s33, 0x800000
	s_mov_b32 s34, 0x2aaaaaab
	s_movk_i32 s35, 0xc0
	s_movk_i32 s36, 0x70
	s_movk_i32 s37, 0x60
	s_movk_i32 s38, 0x80
	s_movk_i32 s39, 0xa0
	s_movk_i32 s40, 0xe0
	s_movk_i32 s41, 0x100
	s_movk_i32 s42, 0x120
	s_movk_i32 s43, 0x140
	s_movk_i32 s44, 0x160
	s_mov_b32 s45, 0x6004000
	s_mov_b32 s46, 0x6006000
	s_mov_b32 s47, 0x42ddb3d8
	s_mov_b64 s[16:17], 0x6000
	s_mov_b64 s[18:19], 0x4000
	s_movk_i32 s48, 0x2000
	s_mov_b32 s49, 0x7ffffff0
	s_movk_i32 s50, 0x3f0
	s_mov_b32 s51, 0x8004000
	s_mov_b32 s52, 0x8006000
	s_movk_i32 s53, 0x1000
	s_movk_i32 s54, 0x3000
	s_mov_b32 s55, 0x8000
	s_mov_b32 s56, 0x9000
	s_mov_b32 s57, 0xa000
	s_mov_b32 s58, 0xb000
	s_mov_b32 s59, 0x10000
	s_mov_b32 s60, 0x11000
	s_mov_b32 s61, 0x12000
	s_mov_b32 s62, 0x13000
	s_mov_b32 s63, 0x19000
	s_mov_b32 s64, 0x1a000
	s_mov_b32 s65, 0x1b000
	s_add_i32 s66, 16, 0x14000
	v_xor_b32_e32 v180, 32, v179
	v_add_u32_e32 v181, 64, v0
	v_mov_b32_e32 v182, 0x50000
	s_mov_b32 s67, s83
	s_branch .LBB0_1145

.LBB0_1174:
	s_setprio 0
	s_cmp_lt_i32 s87, 10
	s_cbranch_scc1 .LBB0_1228
	s_waitcnt vmcnt(0)
	s_waitcnt vmcnt(0) lgkmcnt(0)
	s_barrier
	s_and_saveexec_b64 s[4:5], s[84:85]
	s_cbranch_execz .LBB0_1227
	v_mov_b32_e32 v0, 0
	s_waitcnt vmcnt(0) expcnt(0) lgkmcnt(0)
	ds_read_b32 v2, v0
	ds_read_b32 v1, v0 offset:4
	s_waitcnt lgkmcnt(1)
	v_cmp_ne_u32_e32 vcc, 0, v2
	s_cbranch_vccnz .LBB0_1191
	s_add_u32 s6, s76, 0x19400200
	s_addc_u32 s7, s77, 0
	s_add_u32 s8, s76, 0x19400400
	s_addc_u32 s9, s77, 0
	s_add_u32 s10, s76, 0x19400500
	s_addc_u32 s11, s77, 0
	s_add_u32 s12, s76, 0x19400600
	s_addc_u32 s13, s77, 0
	s_add_u32 s14, s76, 0x19400700
	s_addc_u32 s15, s77, 0
	s_add_u32 s16, s76, 0x19400800
	s_addc_u32 s17, s77, 0
	s_add_u32 s18, s76, 0x19400900
	s_addc_u32 s19, s77, 0
	s_add_u32 s20, s76, 0x19400a00
	s_addc_u32 s21, s77, 0
	s_add_u32 s22, s76, 0x19400b00
	s_addc_u32 s23, s77, 0
	s_add_u32 s24, s76, 0x19400c00
	s_addc_u32 s25, s77, 0
	s_add_u32 s26, s76, 0x19400d00
	s_addc_u32 s27, s77, 0
	s_add_u32 s28, s76, 0x19400e00
	s_addc_u32 s29, s77, 0
	s_add_u32 s30, s76, 0x19400f00
	s_addc_u32 s31, s77, 0
	s_add_u32 s34, s76, 0x19401000
	s_addc_u32 s35, s77, 0
	s_add_u32 s36, s76, 0x19401100
	s_addc_u32 s37, s77, 0
	s_add_u32 s38, s76, 0x19401200
	s_addc_u32 s39, s77, 0
	s_mul_i32 s0, s81, s82
	s_add_u32 s40, s76, 0x19401300
	s_mul_i32 s0, s0, s80
	s_addc_u32 s41, s77, 0
	s_mov_b32 s1, 1
	s_branch .LBB0_1179
